# scan: one static s_setprio 1 for the loader waves (younger half) around the loader loop
# baseline (speedup 1.0000x reference)
; #define LAS __attribute__((address_space(3)))
; __device__ __forceinline__ size_t PIX(int row, int col) { return (size_t)(col >> 7) * PSLOT + (size_t)row * 128 + (col & 127); }
; __device__ void scan_chain(const Params& p, int l, int chain, int vhalf, LAS unsigned char* lds) {
;     ...
;         const int lw = w - 4;
;         const int r16 = lane >> 4, s16 = lane & 15;
;         size_t qoff[2], koff[2];
; #pragma unroll
;         for (int i = 0; i < 2; ++i) { const int row = 8 * lw + 4 * i + r16; qoff[i] = (size_t)row * qpitch + ((s16 ^ (row & 15)) * 8);
;             koff[i] = PIX(4 * (2 * lw + i) + r16, dir * 512 + h * 128) + s16 * 8; }
;         const size_t voff = PIX(16 * vhalf + 4 * lw + r16, 1024 + h * 128) + s16 * 8;
;         const float* dsrc = (const float*)(p.ws + WS_DS) + (size_t)chain * NCH * 128 + (lw & 1) * 64 + lane;
;         const int orow = 8 * lw + (lane >> 3);
;         const size_t ooff = (size_t)h * PSLOT + (size_t)orow * 128 + 64 * vhalf + (((lane & 7) ^ (orow & 7)) * 8);
;         const bf16_t* OFBc = (const bf16_t*)(p.ws + WS_OFB) + (size_t)dir * NROW * 512;
;         auto issue = [&](int s) {
;             const int sc = s < NCH ? s : NCH - 1;
;             const int c = chunk_of(sc), R0 = row0_of(c);
;             LAS unsigned char* st = lds + (s % NSTAGE) * ST_BYTES;
;             const bf16_t* qrow = qb + (size_t)R0 * qpitch; const bf16_t* krow = P + (size_t)R0 * 128;
; #pragma unroll
;             for (int i = 0; i < 2; ++i) {
;                 __builtin_amdgcn_global_load_lds((const unsigned*)(qrow + qoff[i]), (LAS unsigned*)(st + ST_Q + (2 * lw + i) * 1024), 16, 0, 0);
;                 __builtin_amdgcn_global_load_lds((const unsigned*)(krow + koff[i]), (LAS unsigned*)(st + ST_K + (2 * lw + i) * 1024), 16, 0, 0);
;             }
;             __builtin_amdgcn_global_load_lds((const unsigned*)(krow + voff), (LAS unsigned*)(st + ST_V + lw * 1024), 16, 0, 0);
;             __builtin_amdgcn_global_load_lds((const unsigned*)(dsrc + (size_t)c * 128), (LAS unsigned*)(st + ST_D + (lw & 1) * 256), 4, 0, 0);
;             __builtin_amdgcn_global_load_lds((const unsigned*)(OFBc + (size_t)R0 * 128 + ooff), (LAS unsigned*)(st + ST_O + lw * 1024), 16, 0, 0);
;         };
;         issue(0); issue(1); issue(2); issue(3); issue(4);
.LBB0_387:
	s_and_b64 vcc, exec, s[0:1]
	s_cbranch_vccz .LBB0_391
	s_add_i32 s6, s2, -4
	s_lshl_b32 s7, s6, 3
	v_or_b32_e32 v4, s7, v53
	v_mov_b32_e32 v5, v8
	v_lshlrev_b32_e32 v12, 3, v54
	v_readlane_b32 s0, v241, 48
	v_lshlrev_b64 v[2:3], 7, v[4:5]
	v_bitop3_b32 v0, s7, v9, v53 bitop3:0x36
	v_or_b32_e32 v10, 4, v4
	v_mov_b32_e32 v11, v8
	v_bitop3_b32 v4, v4, v9, 4 bitop3:0x36
	v_or_b32_e32 v6, s0, v12
	v_lshlrev_b32_e32 v0, 3, v0
	s_movk_i32 s0, 0x78
	v_lshlrev_b64 v[10:11], 7, v[10:11]
	v_lshlrev_b32_e32 v4, 3, v4
	v_and_or_b32 v0, v0, s0, v2
	v_and_or_b32 v4, v4, s0, v10
	s_lshl_b32 s0, s6, 2
	v_readlane_b32 s1, v242, 12
	v_mov_b32_e32 v7, v8
	s_add_i32 s0, s0, s1
	v_mov_b32_e32 v1, v3
	v_lshl_add_u64 v[2:3], v[2:3], 0, v[6:7]
	v_mov_b32_e32 v5, v11
	v_lshl_add_u64 v[6:7], v[10:11], 0, v[6:7]
	v_or_b32_e32 v10, s0, v53
	v_mov_b32_e32 v11, v8
	v_readlane_b32 s0, v241, 49
	v_lshlrev_b64 v[10:11], 7, v[10:11]
	v_readlane_b32 s1, v241, 50
	v_mov_b32_e32 v13, v8
	v_lshrrev_b32_e32 v16, 3, v52
	v_lshl_add_u64 v[10:11], v[10:11], 0, s[0:1]
	s_and_b32 s0, s5, 64
	s_lshl_b32 s0, s0, 2
	v_readlane_b32 s1, v242, 14
	s_add_u32 s0, s1, s0
	v_readlane_b32 s1, v242, 16
	v_or_b32_e32 v10, v10, v12
	s_addc_u32 s1, s1, 0
	v_lshlrev_b32_e32 v12, 2, v52
	v_lshl_add_u64 v[12:13], s[0:1], 0, v[12:13]
	v_or_b32_e32 v14, s7, v16
	v_mov_b32_e32 v15, v8
	v_readlane_b32 s0, v241, 51
	v_lshlrev_b64 v[14:15], 7, v[14:15]
	v_readlane_b32 s1, v241, 52
	v_readlane_b32 s10, v241, 26
	v_readlane_b32 s11, v241, 27
	v_lshl_add_u64 v[24:25], v[14:15], 0, s[0:1]
	s_lshl_b32 s0, s6, 11
	v_lshlrev_b64 v[14:15], 1, v[0:1]
	s_add_i32 s7, s0, 16
	v_bitop3_b32 v9, v16, v9, 7 bitop3:0x78
	v_lshl_add_u64 v[16:17], s[10:11], 0, v[14:15]
	s_mov_b32 m0, s7
	v_readlane_b32 s12, v242, 19
	global_load_lds_dwordx4 v[16:17], off
	v_lshlrev_b64 v[16:17], 1, v[2:3]
	v_readlane_b32 s13, v242, 20
	s_add_i32 s8, s7, 0x2000
	s_mov_b32 m0, s8
	v_lshl_add_u64 v[18:19], s[12:13], 0, v[16:17]
	global_load_lds_dwordx4 v[18:19], off
	v_lshlrev_b64 v[18:19], 1, v[4:5]
	s_add_i32 s9, s7, 0x400
	v_lshl_add_u64 v[20:21], s[10:11], 0, v[18:19]
	s_mov_b32 m0, s9
	s_add_i32 s10, s7, 0x2400
	global_load_lds_dwordx4 v[20:21], off
	v_lshlrev_b64 v[20:21], 1, v[6:7]
	v_lshl_add_u64 v[22:23], s[12:13], 0, v[20:21]
	s_mov_b32 m0, s10
	s_lshl_b32 s1, s6, 10
	global_load_lds_dwordx4 v[22:23], off
	v_lshlrev_b64 v[22:23], 1, v[10:11]
	s_add_i32 s6, s1, 16
	s_lshl_b32 s2, s2, 8
	v_lshl_add_u64 v[26:27], s[12:13], 0, v[22:23]
	s_add_i32 s11, s6, 0x4000
	v_readlane_b32 s12, v241, 53
	s_and_b32 s5, s2, 0x100
	s_mov_b32 m0, s11
	v_readlane_b32 s13, v241, 54
	s_add_i32 s2, s5, 16
	v_lshl_or_b32 v24, v9, 3, v24
	global_load_lds_dwordx4 v[26:27], off
	v_lshl_add_u64 v[26:27], v[12:13], 0, s[12:13]
	s_add_i32 s12, s2, 0x6000
	v_readlane_b32 s14, v242, 21
	s_mov_b32 m0, s12
	v_lshlrev_b64 v[24:25], 1, v[24:25]
	v_readlane_b32 s15, v242, 22
	s_add_i32 s13, s6, 0x5000
	v_readlane_b32 s16, v241, 28
	global_load_lds_dword v[26:27], off
	v_lshl_add_u64 v[26:27], s[14:15], 0, v[24:25]
	s_mov_b32 m0, s13
	v_readlane_b32 s17, v241, 29
	s_add_i32 s14, s7, 0x6200
	v_readlane_b32 s18, v242, 25
	global_load_lds_dwordx4 v[26:27], off
	v_lshl_add_u64 v[26:27], s[16:17], 0, v[14:15]
	s_mov_b32 m0, s14
	v_readlane_b32 s19, v242, 26
	s_add_i32 s15, s7, 0x8200
	global_load_lds_dwordx4 v[26:27], off
	v_lshl_add_u64 v[26:27], s[18:19], 0, v[16:17]
	s_mov_b32 m0, s15
	v_readlane_b32 s20, v241, 55
	global_load_lds_dwordx4 v[26:27], off
	v_lshl_add_u64 v[26:27], s[16:17], 0, v[18:19]
	s_add_i32 s16, s7, 0x6600
	s_mov_b32 m0, s16
	s_add_i32 s17, s7, 0x8600
	global_load_lds_dwordx4 v[26:27], off
	v_lshl_add_u64 v[26:27], s[18:19], 0, v[20:21]
	s_mov_b32 m0, s17
	v_readlane_b32 s21, v241, 56
	global_load_lds_dwordx4 v[26:27], off
	v_lshl_add_u64 v[26:27], s[18:19], 0, v[22:23]
	s_add_i32 s18, s6, 0xa200
	s_mov_b32 m0, s18
	s_add_i32 s19, s2, 0xc200
	global_load_lds_dwordx4 v[26:27], off
	v_lshl_add_u64 v[26:27], v[12:13], 0, s[20:21]
	v_readlane_b32 s20, v242, 27
	s_mov_b32 m0, s19
	v_readlane_b32 s21, v242, 28
	global_load_lds_dword v[26:27], off
	s_nop 0
	v_lshl_add_u64 v[26:27], s[20:21], 0, v[24:25]
	s_add_i32 s20, s6, 0xb200
	v_readlane_b32 s38, v241, 30
	s_mov_b32 m0, s20
	v_readlane_b32 s39, v241, 31
	v_readlane_b32 s22, v242, 29
	global_load_lds_dwordx4 v[26:27], off
	v_lshl_add_u64 v[26:27], s[38:39], 0, v[14:15]
	s_add_i32 m0, s7, 0xc400
	v_readlane_b32 s23, v242, 30
	global_load_lds_dwordx4 v[26:27], off
	s_nop 0
	v_lshl_add_u64 v[26:27], s[22:23], 0, v[16:17]
	s_add_i32 m0, s7, 0xe400
	s_nop 0
	global_load_lds_dwordx4 v[26:27], off
	v_lshl_add_u64 v[26:27], s[38:39], 0, v[18:19]
	s_add_i32 m0, s7, 0xc800
	v_readlane_b32 s38, v241, 32
	global_load_lds_dwordx4 v[26:27], off
	v_lshl_add_u64 v[26:27], s[22:23], 0, v[20:21]
	s_add_i32 m0, s7, 0xe800
	v_readlane_b32 s39, v241, 33
	global_load_lds_dwordx4 v[26:27], off
	v_lshl_add_u64 v[26:27], s[22:23], 0, v[22:23]
	v_readlane_b32 s22, v241, 57
	s_add_i32 m0, s6, 0x10400
	v_readlane_b32 s23, v241, 58
	global_load_lds_dwordx4 v[26:27], off
	s_nop 0
	v_lshl_add_u64 v[26:27], v[12:13], 0, s[22:23]
	v_readlane_b32 s22, v242, 31
	s_add_i32 m0, s2, 0x12400
	v_readlane_b32 s23, v242, 32
	global_load_lds_dword v[26:27], off
	s_nop 0
	v_lshl_add_u64 v[26:27], s[22:23], 0, v[24:25]
	s_add_i32 m0, s6, 0x11400
	v_readlane_b32 s22, v242, 33
	global_load_lds_dwordx4 v[26:27], off
	v_lshl_add_u64 v[26:27], s[38:39], 0, v[14:15]
	s_add_i32 m0, s7, 0x12600
	v_readlane_b32 s23, v242, 34
	global_load_lds_dwordx4 v[26:27], off
	s_nop 0
	v_lshl_add_u64 v[26:27], s[22:23], 0, v[16:17]
	s_add_i32 m0, s7, 0x14600
; #define LAS __attribute__((address_space(3)))
; __device__ void scan_chain(const Params& p, int l, int chain, int vhalf, LAS unsigned char* lds) {
;     ...
;         auto issue = [&](int s) {
;             const int sc = s < NCH ? s : NCH - 1;
;             const int c = chunk_of(sc), R0 = row0_of(c);
;             LAS unsigned char* st = lds + (s % NSTAGE) * ST_BYTES;
;             const bf16_t* qrow = qb + (size_t)R0 * qpitch; const bf16_t* krow = P + (size_t)R0 * 128;
; #pragma unroll
;             for (int i = 0; i < 2; ++i) {
;                 __builtin_amdgcn_global_load_lds((const unsigned*)(qrow + qoff[i]), (LAS unsigned*)(st + ST_Q + (2 * lw + i) * 1024), 16, 0, 0);
;                 __builtin_amdgcn_global_load_lds((const unsigned*)(krow + koff[i]), (LAS unsigned*)(st + ST_K + (2 * lw + i) * 1024), 16, 0, 0);
;             }
;             __builtin_amdgcn_global_load_lds((const unsigned*)(krow + voff), (LAS unsigned*)(st + ST_V + lw * 1024), 16, 0, 0);
;             __builtin_amdgcn_global_load_lds((const unsigned*)(dsrc + (size_t)c * 128), (LAS unsigned*)(st + ST_D + (lw & 1) * 256), 4, 0, 0);
;             __builtin_amdgcn_global_load_lds((const unsigned*)(OFBc + (size_t)R0 * 128 + ooff), (LAS unsigned*)(st + ST_O + lw * 1024), 16, 0, 0);
;         };
;         issue(0); issue(1); issue(2); issue(3); issue(4);
;         asm volatile("s_waitcnt vmcnt(28)" ::: "memory");
;         __builtin_amdgcn_s_barrier();
;         for (int s = 0; s < NCH; ++s) {
;             issue(s + 5);
;             asm volatile("s_waitcnt vmcnt(28)" ::: "memory");
;             __builtin_amdgcn_s_barrier();
;         }
	s_nop 0
	global_load_lds_dwordx4 v[26:27], off
	v_lshl_add_u64 v[26:27], s[38:39], 0, v[18:19]
	s_add_i32 m0, s7, 0x12a00
	v_readlane_b32 s38, v241, 34
	global_load_lds_dwordx4 v[26:27], off
	v_lshl_add_u64 v[26:27], s[22:23], 0, v[20:21]
	s_add_i32 m0, s7, 0x14a00
	v_readlane_b32 s39, v241, 35
	global_load_lds_dwordx4 v[26:27], off
	v_lshl_add_u64 v[26:27], s[22:23], 0, v[22:23]
	v_readlane_b32 s22, v241, 59
	s_add_i32 m0, s6, 0x16600
	v_readlane_b32 s23, v241, 60
	global_load_lds_dwordx4 v[26:27], off
	s_nop 0
	v_lshl_add_u64 v[26:27], v[12:13], 0, s[22:23]
	v_readlane_b32 s22, v242, 35
	s_add_i32 m0, s2, 0x18600
	v_readlane_b32 s23, v242, 36
	global_load_lds_dword v[26:27], off
	s_nop 0
	v_lshl_add_u64 v[26:27], s[22:23], 0, v[24:25]
	s_add_i32 m0, s6, 0x17600
	v_readlane_b32 s22, v242, 37
	global_load_lds_dwordx4 v[26:27], off
	v_lshl_add_u64 v[26:27], s[38:39], 0, v[14:15]
	s_add_i32 m0, s7, 0x18800
	v_readlane_b32 s23, v242, 38
	global_load_lds_dwordx4 v[26:27], off
	s_nop 0
	v_lshl_add_u64 v[26:27], s[22:23], 0, v[16:17]
	s_add_i32 m0, s7, 0x1a800
	s_nop 0
	global_load_lds_dwordx4 v[26:27], off
	v_lshl_add_u64 v[26:27], s[38:39], 0, v[18:19]
	s_add_i32 m0, s7, 0x18c00
	v_readlane_b32 s38, v241, 36
	global_load_lds_dwordx4 v[26:27], off
	v_lshl_add_u64 v[26:27], s[22:23], 0, v[20:21]
	s_add_i32 m0, s7, 0x1ac00
	v_readlane_b32 s39, v241, 37
	global_load_lds_dwordx4 v[26:27], off
	v_lshl_add_u64 v[26:27], s[22:23], 0, v[22:23]
	v_readlane_b32 s22, v241, 61
	s_add_i32 m0, s6, 0x1c800
	v_readlane_b32 s23, v241, 62
	global_load_lds_dwordx4 v[26:27], off
	s_nop 0
	v_lshl_add_u64 v[26:27], v[12:13], 0, s[22:23]
	v_readlane_b32 s22, v242, 41
	s_add_i32 m0, s2, 0x1e800
	v_readlane_b32 s23, v242, 42
	global_load_lds_dword v[26:27], off
	s_nop 0
	v_lshl_add_u64 v[26:27], s[22:23], 0, v[24:25]
	v_readlane_b32 s22, v242, 39
	v_readlane_b32 s23, v242, 40
	s_add_i32 m0, s6, 0x1d800
	s_nop 0
	v_lshl_add_u64 v[24:25], s[22:23], 0, v[24:25]
	v_readlane_b32 s22, v242, 45
	global_load_lds_dwordx4 v[26:27], off
	v_lshl_add_u64 v[26:27], s[38:39], 0, v[14:15]
	s_add_i32 m0, s7, 0x1ea00
	v_readlane_b32 s23, v242, 46
	s_waitcnt vmcnt(28)
	s_barrier
	global_load_lds_dwordx4 v[26:27], off
	v_lshl_add_u64 v[26:27], s[22:23], 0, v[16:17]
	s_add_i32 m0, s7, 0x20a00
	s_nop 0
	global_load_lds_dwordx4 v[26:27], off
	v_lshl_add_u64 v[26:27], s[38:39], 0, v[18:19]
	s_add_i32 m0, s7, 0x1ee00
	s_nop 0
	global_load_lds_dwordx4 v[26:27], off
	v_lshl_add_u64 v[26:27], s[22:23], 0, v[20:21]
	s_add_i32 m0, s7, 0x20e00
	s_nop 0
	global_load_lds_dwordx4 v[26:27], off
	v_lshl_add_u64 v[26:27], s[22:23], 0, v[22:23]
	v_readlane_b32 s22, v241, 63
	s_add_i32 m0, s6, 0x22a00
	v_readlane_b32 s23, v240, 0
	global_load_lds_dwordx4 v[26:27], off
	s_nop 0
	v_lshl_add_u64 v[26:27], v[12:13], 0, s[22:23]
	v_readlane_b32 s22, v242, 43
	s_add_i32 m0, s2, 0x24a00
	v_readlane_b32 s23, v242, 44
	global_load_lds_dword v[26:27], off
	s_nop 0
	v_lshl_add_u64 v[26:27], s[22:23], 1, v[24:25]
	s_add_i32 m0, s6, 0x23a00
	v_readlane_b32 s22, v241, 38
	global_load_lds_dwordx4 v[26:27], off
	v_readlane_b32 s23, v241, 39
	s_mov_b32 m0, s7
	v_readlane_b32 s6, v242, 49
	v_lshl_add_u64 v[26:27], s[22:23], 0, v[14:15]
	v_readlane_b32 s7, v242, 50
	s_waitcnt vmcnt(28)
	s_barrier
	global_load_lds_dwordx4 v[26:27], off
	v_lshl_add_u64 v[26:27], s[6:7], 0, v[16:17]
	s_mov_b32 m0, s8
	s_nop 0
	global_load_lds_dwordx4 v[26:27], off
	v_lshl_add_u64 v[26:27], s[22:23], 0, v[18:19]
	s_mov_b32 m0, s9
	v_readlane_b32 s8, v241, 42
	global_load_lds_dwordx4 v[26:27], off
	v_lshl_add_u64 v[26:27], s[6:7], 0, v[20:21]
	s_mov_b32 m0, s10
	v_readlane_b32 s9, v241, 43
	global_load_lds_dwordx4 v[26:27], off
	v_lshl_add_u64 v[26:27], s[6:7], 0, v[22:23]
	v_readlane_b32 s6, v240, 1
	s_mov_b32 m0, s11
	v_readlane_b32 s7, v240, 2
	global_load_lds_dwordx4 v[26:27], off
	s_nop 0
	v_lshl_add_u64 v[26:27], v[12:13], 0, s[6:7]
	v_readlane_b32 s6, v242, 47
	s_mov_b32 m0, s12
	v_readlane_b32 s7, v242, 48
	global_load_lds_dword v[26:27], off
	s_nop 0
	v_lshl_add_u64 v[26:27], s[6:7], 1, v[24:25]
	s_mov_b32 m0, s13
	v_readlane_b32 s6, v242, 53
	global_load_lds_dwordx4 v[26:27], off
	v_lshl_add_u64 v[14:15], s[8:9], 0, v[14:15]
	s_mov_b32 m0, s14
	v_readlane_b32 s7, v242, 54
	s_waitcnt vmcnt(28)
	s_barrier
	global_load_lds_dwordx4 v[14:15], off
	v_lshl_add_u64 v[14:15], s[6:7], 0, v[16:17]
	s_mov_b32 m0, s15
	v_readlane_b32 s14, v242, 23
	global_load_lds_dwordx4 v[14:15], off
	v_lshl_add_u64 v[14:15], s[8:9], 0, v[18:19]
	s_mov_b32 m0, s16
	v_readlane_b32 s12, v242, 17
	global_load_lds_dwordx4 v[14:15], off
	v_lshl_add_u64 v[14:15], s[6:7], 0, v[20:21]
	s_mov_b32 m0, s17
	v_readlane_b32 s15, v242, 24
	global_load_lds_dwordx4 v[14:15], off
	v_lshl_add_u64 v[14:15], s[6:7], 0, v[22:23]
	v_readlane_b32 s6, v240, 3
	s_mov_b32 m0, s18
	v_readlane_b32 s7, v240, 4
	global_load_lds_dwordx4 v[14:15], off
	s_nop 0
	v_lshl_add_u64 v[14:15], v[12:13], 0, s[6:7]
	v_readlane_b32 s6, v242, 51
	s_mov_b32 m0, s19
	v_readlane_b32 s7, v242, 52
	global_load_lds_dword v[14:15], off
	s_nop 0
	v_lshl_add_u64 v[14:15], s[6:7], 1, v[24:25]
	s_mov_b32 m0, s20
	s_mov_b32 s6, 8
	global_load_lds_dwordx4 v[14:15], off
	s_waitcnt vmcnt(28)
	v_readlane_b32 s13, v241, 40
	v_readlane_b32 s16, v241, 41
	s_barrier
	s_setprio 1
; __device__ void scan_chain(const Params& p, int l, int chain, int vhalf, LAS unsigned char* lds) {
;     ...
;         for (int s = 0; s < NCH; ++s) {
;             issue(s + 5);
;             asm volatile("s_waitcnt vmcnt(28)" ::: "memory");
;             __builtin_amdgcn_s_barrier();
;         }
;         asm volatile("s_waitcnt vmcnt(0)" ::: "memory");
.LBB0_389:
	s_min_u32 s2, s6, 0x87
	s_sub_i32 s7, 0x8f, s2
	s_and_b64 s[8:9], s[14:15], exec
	s_cselect_b32 s2, s2, s7
	s_lshl_b32 s7, s2, 5
	s_cmp_lt_u32 s2, 8
	s_cselect_b32 s8, 8, 12
	s_cselect_b32 s9, 0x8000, s91
	s_and_b32 s10, s6, 0xff
	s_lshl_b32 s8, s12, s8
	s_add_i32 s7, s9, s7
	s_mulk_i32 s10, 0xab
	s_add_i32 s8, s7, s8
	s_lshr_b32 s7, s10, 10
	s_mul_i32 s7, s7, 6
	s_sub_i32 s7, s6, s7
	s_and_b32 s7, s7, 0xff
	s_ashr_i32 s9, s8, 31
	s_mulk_i32 s7, 0x6200
	s_lshl_b64 s[8:9], s[8:9], 8
	s_add_i32 s7, s7, 16
	s_add_u32 s10, s13, s8
	s_addc_u32 s11, s16, s9
	v_lshl_add_u64 v[14:15], v[24:25], 0, s[8:9]
	s_add_u32 s8, s82, s8
	v_lshl_add_u64 v[16:17], v[0:1], 1, s[10:11]
	v_lshl_add_u64 v[18:19], v[4:5], 1, s[10:11]
	s_addc_u32 s9, s83, s9
	s_add_i32 s10, s7, s0
	s_mov_b32 m0, s10
	v_lshl_add_u64 v[20:21], v[2:3], 1, s[8:9]
	global_load_lds_dwordx4 v[16:17], off
	s_add_i32 m0, s10, 0x2000
	s_add_i32 s11, s7, s1
	global_load_lds_dwordx4 v[20:21], off
	s_add_i32 m0, s10, 0x400
	v_lshl_add_u64 v[22:23], v[6:7], 1, s[8:9]
	global_load_lds_dwordx4 v[18:19], off
	s_add_i32 m0, s10, 0x2400
	s_lshl_b32 s2, s2, 9
	s_add_i32 s7, s7, s5
	v_lshl_add_u64 v[26:27], v[10:11], 1, s[8:9]
	global_load_lds_dwordx4 v[22:23], off
	s_add_i32 m0, s11, 0x4000
	v_lshl_add_u64 v[28:29], v[12:13], 0, s[2:3]
	global_load_lds_dwordx4 v[26:27], off
	s_add_i32 m0, s7, 0x6000
	s_add_i32 s6, s6, 1
	global_load_lds_dword v[28:29], off
	s_add_i32 m0, s11, 0x5000
	s_cmpk_eq_i32 s6, 0x8d
	global_load_lds_dwordx4 v[14:15], off
	s_waitcnt vmcnt(28)
	s_barrier
	s_cbranch_scc0 .LBB0_389
	s_setprio 0
	s_waitcnt vmcnt(0)
	v_readlane_b32 s14, v244, 49
	v_readlane_b32 s16, v244, 51
	v_readlane_b32 s12, v244, 53
	v_readlane_b32 s15, v244, 50
	v_readlane_b32 s17, v244, 52
	v_readlane_b32 s13, v244, 54
